# GEMM1 tail fill: short blocks take up to 11 weight-transposes tiles instead of 10 (all remaining tiles absorbed there)
# baseline (speedup 1.0000x reference)
.LBB0_441:
	s_barrier
	s_and_saveexec_b64 s[2:3], vcc
	s_cbranch_execz .LBB0_447
	s_cmp_gt_u32 s10, 10
	v_mov_b32_e32 v136, 0x670
	s_cbranch_scc1 .LBB0_446
	s_mov_b64 s[18:19], exec
	v_mbcnt_lo_u32_b32 v136, s18, 0
	v_mbcnt_hi_u32_b32 v136, s19, v136
	v_cmp_eq_u32_e64 s[0:1], 0, v136
	s_and_saveexec_b64 s[4:5], s[0:1]
	s_cbranch_execz .LBB0_445
	s_bcnt1_i32_b64 s0, s[18:19]
	v_mov_b32_e32 v137, s0
	global_atomic_add v137, v135, v137, s[6:7] sc0
